# GEMM K-loop loop-edge edits: back edge rotated into one conditional branch, mid-K hook test shortened and moved out of line, loop head aligned to 64 B
# speedup vs baseline: 1.0072x; 1.0072x over previous
; #define PG8_STAGE(bufoff, gbase, voff) do { _Pragma("unroll") for (int _i = 0; _i < 2; ++_i) \
;         __builtin_amdgcn_global_load_lds((const unsigned*)((const char*)(gbase) + (voff)[_i]), (LAS unsigned*)(lds + (bufoff) + ldsw + _i * 8192), 16, 0, 0); } while (0)
; #define PG8_LDA(dst, b, h) do { _Pragma("unroll") for (int m = 0; m < 4; ++m) _Pragma("unroll") for (int k = 0; k < 2; ++k) dst[m][k] = *(const LAS bf16x8*)(lds + PG8_SA(b, h) + aoff + m * 2048 + k * 1024); } while (0)
; #define PG8_LDB(dst, b, h) do { _Pragma("unroll") for (int n = 0; n < 2; ++n) _Pragma("unroll") for (int k = 0; k < 2; ++k) dst[n][k] = *(const LAS bf16x8*)(lds + PG8_SB(b, h) + boff + n * 2048 + k * 1024); } while (0)
; #define PG8_MMA(ai, bj, At, Bt) do { __builtin_amdgcn_s_setprio(1); _Pragma("unroll") for (int m = 0; m < 4; ++m) _Pragma("unroll") for (int n = 0; n < 2; ++n) _Pragma("unroll") for (int k = 0; k < 2; ++k) \
;         acc[ai][bj][m][n] = __builtin_amdgcn_mfma_f32_16x16x32_bf16(Bt[n][k], At[m][k], acc[ai][bj][m][n], 0, 0, 0); __builtin_amdgcn_s_setprio(0); } while (0)
; template <class Epi, class Sched>
; __device__ __forceinline__ void gemm_phase(LAS unsigned char* lds, const Gemm g, const Sched& S, const Epi& E, const int tid) {
;     ...
; #pragma unroll
;     for (int a = 0; a < 2; ++a)
; #pragma unroll
;         for (int b = 0; b < 2; ++b)
; #pragma unroll
;             for (int m = 0; m < 4; ++m)
; #pragma unroll
;                 for (int n = 0; n < 2; ++n) acc[a][b][m][n] = (f32x4){0.f, 0.f, 0.f, 0.f};
;     ...
;         for (int t = 0; t < nt; t += 2) {
;             const bool last = (t == nt - 2);
;             const char* a1 = cA + (size_t)(t + 1) * kstep;
;             const char* a2 = last ? nA : cA + (size_t)(t + 2) * kstep; const char* b2 = last ? nB : cB + (size_t)(t + 2) * kstep;
;             const char* a3 = a2 + kstep; const char* b3 = b2 + kstep;
;             if (last && has_next) S.a_ready(nxt);
;             if (E.rs2 && t == nt / 2) { PG8_SCHED; E.mid(acc, cur, wr, fr); PG8_SCHED; }
;             PG8_LDB(B0, 0, 0); PG8_SCHED; PG8_LDA(At, 0, 0); PG8_STAGE(PG8_SA(1, 1), a1 + hstep, voffA);
;             PG8_WAIT_L(8); PG8_BAR; PG8_WAIT_L(0); PG8_MMA(0, 0, At, B0); PG8_BAR; PG8_SCHED;
;             PG8_LDB(B1, 0, 1); PG8_STAGE(PG8_SB(0, 0), b2, voffB);
;             PG8_BAR; PG8_WAIT_L(0); PG8_MMA(0, 1, At, B1); PG8_BAR;
.LBB0_420:
	s_add_u32 s69, s34, 0x100
	s_addc_u32 s70, s35, 0
	s_add_u32 s4, s2, 0x80
	v_mov_b32_e32 v3, v2
	v_lshl_add_u32 v184, s33, 8, v226
	s_addc_u32 s5, s3, 0
	v_mov_b32_e32 v0, v2
	v_mov_b32_e32 v1, v2
	v_mov_b64_e32 v[6:7], v[2:3]
	v_mov_b64_e32 v[10:11], v[2:3]
	v_mov_b64_e32 v[22:23], v[2:3]
	v_mov_b64_e32 v[26:27], v[2:3]
	v_mov_b64_e32 v[38:39], v[2:3]
	v_mov_b64_e32 v[42:43], v[2:3]
	v_mov_b64_e32 v[54:55], v[2:3]
	v_mov_b64_e32 v[58:59], v[2:3]
	v_mov_b64_e32 v[14:15], v[2:3]
	v_mov_b64_e32 v[18:19], v[2:3]
	v_mov_b64_e32 v[30:31], v[2:3]
	v_mov_b64_e32 v[34:35], v[2:3]
	v_mov_b64_e32 v[46:47], v[2:3]
	v_mov_b64_e32 v[50:51], v[2:3]
	v_mov_b64_e32 v[62:63], v[2:3]
	v_mov_b64_e32 v[66:67], v[2:3]
	v_mov_b64_e32 v[70:71], v[2:3]
	v_mov_b64_e32 v[74:75], v[2:3]
	v_mov_b64_e32 v[86:87], v[2:3]
	v_mov_b64_e32 v[90:91], v[2:3]
	v_mov_b64_e32 v[102:103], v[2:3]
	v_mov_b64_e32 v[106:107], v[2:3]
	v_mov_b64_e32 v[118:119], v[2:3]
	v_mov_b64_e32 v[122:123], v[2:3]
	v_mov_b64_e32 v[78:79], v[2:3]
	v_mov_b64_e32 v[82:83], v[2:3]
	v_mov_b64_e32 v[94:95], v[2:3]
	v_mov_b64_e32 v[98:99], v[2:3]
	v_mov_b64_e32 v[110:111], v[2:3]
	v_mov_b64_e32 v[114:115], v[2:3]
	v_mov_b64_e32 v[126:127], v[2:3]
	v_mov_b64_e32 v[130:131], v[2:3]
	v_or_b32_e32 v182, 16, v184
	v_or_b32_e32 v180, 32, v184
	v_or_b32_e32 v178, 48, v184
	v_add_u32_e32 v176, 0x80, v184
	v_add_u32_e32 v174, 0x90, v184
	v_add_u32_e32 v172, 0xa0, v184
	v_add_u32_e32 v170, 0xb0, v184
	v_lshl_add_u64 v[132:133], s[4:5], 0, v[166:167]
	v_lshl_add_u64 v[134:135], s[4:5], 0, v[168:169]
	s_mov_b32 s34, 0
	s_mov_b64 s[4:5], 0
	v_mov_b64_e32 v[4:5], v[0:1]
	v_mov_b64_e32 v[8:9], v[0:1]
	v_mov_b64_e32 v[20:21], v[0:1]
	v_mov_b64_e32 v[24:25], v[0:1]
	v_mov_b64_e32 v[36:37], v[0:1]
	v_mov_b64_e32 v[40:41], v[0:1]
	v_mov_b64_e32 v[52:53], v[0:1]
	v_mov_b64_e32 v[56:57], v[0:1]
	v_mov_b64_e32 v[12:13], v[0:1]
	v_mov_b64_e32 v[16:17], v[0:1]
	v_mov_b64_e32 v[28:29], v[0:1]
	v_mov_b64_e32 v[32:33], v[0:1]
	v_mov_b64_e32 v[44:45], v[0:1]
	v_mov_b64_e32 v[48:49], v[0:1]
	v_mov_b64_e32 v[60:61], v[0:1]
	v_mov_b64_e32 v[64:65], v[0:1]
	v_mov_b64_e32 v[68:69], v[0:1]
	v_mov_b64_e32 v[72:73], v[0:1]
	v_mov_b64_e32 v[84:85], v[0:1]
	v_mov_b64_e32 v[88:89], v[0:1]
	v_mov_b64_e32 v[100:101], v[0:1]
	v_mov_b64_e32 v[104:105], v[0:1]
	v_mov_b64_e32 v[116:117], v[0:1]
	v_mov_b64_e32 v[120:121], v[0:1]
	v_mov_b64_e32 v[76:77], v[0:1]
	v_mov_b64_e32 v[80:81], v[0:1]
	v_mov_b64_e32 v[92:93], v[0:1]
	v_mov_b64_e32 v[96:97], v[0:1]
	v_mov_b64_e32 v[108:109], v[0:1]
	v_mov_b64_e32 v[112:113], v[0:1]
	v_mov_b64_e32 v[124:125], v[0:1]
	v_mov_b64_e32 v[128:129], v[0:1]
	.p2align 6
.LBB0_421:
	s_cmp_eq_u32 s62, s34
	s_cbranch_scc1 .Lmy_midchk
.LBB0_423:
	s_add_i32 s33, s34, 2
	v_add_u32_e32 v0, s42, v227
	s_add_u32 s35, s2, s4
	ds_read_b128 v[136:139], v0
	ds_read_b128 v[140:143], v0 offset:1024
	ds_read_b128 v[144:147], v0 offset:2048
	ds_read_b128 v[148:151], v0 offset:3072
	s_addc_u32 s36, s3, s5
	s_add_u32 s37, s35, 0x100
	s_addc_u32 s35, s36, 0
	s_add_u32 s36, s69, s4
	s_addc_u32 s71, s70, s5
	s_cmp_eq_u32 s61, s34
	s_cselect_b32 s35, s31, s35
	s_cselect_b32 s34, s30, s37
	s_cselect_b32 s37, s1, s71
	s_cselect_b32 s36, s0, s36
	v_lshl_add_u64 v[0:1], v[134:135], 0, s[4:5]
	s_add_i32 m0, s45, 0xc000
	ds_read_b128 v[152:155], v229
	ds_read_b128 v[186:189], v229 offset:1024
	ds_read_b128 v[190:193], v229 offset:2048
	ds_read_b128 v[194:197], v229 offset:3072
	ds_read_b128 v[198:201], v229 offset:4096
	ds_read_b128 v[202:205], v229 offset:5120
	ds_read_b128 v[210:213], v229 offset:6144
	ds_read_b128 v[214:217], v229 offset:7168
	global_load_lds_dwordx4 v[0:1], off
	v_lshl_add_u64 v[0:1], v[132:133], 0, s[4:5]
	s_add_i32 m0, s45, 0xe000
	s_nop 0
	global_load_lds_dwordx4 v[0:1], off
	s_waitcnt lgkmcnt(8)
	s_barrier
	s_waitcnt lgkmcnt(0)
	s_setprio 1
	s_waitcnt lgkmcnt(0)
	v_mfma_f32_16x16x32_bf16 v[128:131], v[136:139], v[152:155], v[128:131]
	v_mfma_f32_16x16x32_bf16 v[124:127], v[144:147], v[152:155], v[124:127]
	v_mfma_f32_16x16x32_bf16 v[112:115], v[136:139], v[190:193], v[112:115]
	v_mfma_f32_16x16x32_bf16 v[108:111], v[144:147], v[190:193], v[108:111]
	v_mfma_f32_16x16x32_bf16 v[96:99], v[136:139], v[198:201], v[96:99]
	v_mfma_f32_16x16x32_bf16 v[92:95], v[144:147], v[198:201], v[92:95]
	v_mfma_f32_16x16x32_bf16 v[80:83], v[136:139], v[210:213], v[80:83]
	v_mfma_f32_16x16x32_bf16 v[76:79], v[144:147], v[210:213], v[76:79]
	v_mfma_f32_16x16x32_bf16 v[128:131], v[140:143], v[186:189], v[128:131]
	v_mfma_f32_16x16x32_bf16 v[124:127], v[148:151], v[186:189], v[124:127]
	v_mfma_f32_16x16x32_bf16 v[112:115], v[140:143], v[194:197], v[112:115]
	v_mfma_f32_16x16x32_bf16 v[108:111], v[148:151], v[194:197], v[108:111]
	v_mfma_f32_16x16x32_bf16 v[96:99], v[140:143], v[202:205], v[96:99]
	v_mfma_f32_16x16x32_bf16 v[92:95], v[148:151], v[202:205], v[92:95]
	v_mfma_f32_16x16x32_bf16 v[80:83], v[140:143], v[214:217], v[80:83]
	v_mfma_f32_16x16x32_bf16 v[76:79], v[148:151], v[214:217], v[76:79]
	s_setprio 0
	s_barrier
	v_add_u32_e32 v0, s47, v227
	s_mov_b32 m0, s43
	ds_read_b128 v[218:221], v0
	ds_read_b128 v[230:233], v0 offset:1024
	ds_read_b128 v[234:237], v0 offset:2048
	ds_read_b128 v[238:241], v0 offset:3072
	v_lshl_add_u64 v[0:1], s[36:37], 0, v[160:161]
	global_load_lds_dwordx4 v[0:1], off
	v_lshl_add_u64 v[242:243], s[36:37], 0, v[164:165]
	s_mov_b32 m0, s44
	s_nop 0
	global_load_lds_dwordx4 v[242:243], off
	s_barrier
; #define PG8_STAGE(bufoff, gbase, voff) do { _Pragma("unroll") for (int _i = 0; _i < 2; ++_i) \
;         __builtin_amdgcn_global_load_lds((const unsigned*)((const char*)(gbase) + (voff)[_i]), (LAS unsigned*)(lds + (bufoff) + ldsw + _i * 8192), 16, 0, 0); } while (0)
; #define PG8_LDA(dst, b, h) do { _Pragma("unroll") for (int m = 0; m < 4; ++m) _Pragma("unroll") for (int k = 0; k < 2; ++k) dst[m][k] = *(const LAS bf16x8*)(lds + PG8_SA(b, h) + aoff + m * 2048 + k * 1024); } while (0)
; #define PG8_LDB(dst, b, h) do { _Pragma("unroll") for (int n = 0; n < 2; ++n) _Pragma("unroll") for (int k = 0; k < 2; ++k) dst[n][k] = *(const LAS bf16x8*)(lds + PG8_SB(b, h) + boff + n * 2048 + k * 1024); } while (0)
; #define PG8_MMA(ai, bj, At, Bt) do { __builtin_amdgcn_s_setprio(1); _Pragma("unroll") for (int m = 0; m < 4; ++m) _Pragma("unroll") for (int n = 0; n < 2; ++n) _Pragma("unroll") for (int k = 0; k < 2; ++k) \
;         acc[ai][bj][m][n] = __builtin_amdgcn_mfma_f32_16x16x32_bf16(Bt[n][k], At[m][k], acc[ai][bj][m][n], 0, 0, 0); __builtin_amdgcn_s_setprio(0); } while (0)
; #define PG8_WAIT_V(n) asm volatile("s_waitcnt vmcnt(" #n ")" ::: "memory")
; #define PG8_WAIT_L(n) asm volatile("s_waitcnt lgkmcnt(" #n ")" ::: "memory")
; #define PG8_BAR __builtin_amdgcn_s_barrier()
; #define PG8_SCHED __builtin_amdgcn_sched_barrier(0)
; template <class Epi, class Sched>
; __device__ __forceinline__ void gemm_phase(LAS unsigned char* lds, const Gemm g, const Sched& S, const Epi& E, const int tid) {
;     ...
;             PG8_BAR; PG8_WAIT_L(0); PG8_MMA(0, 1, At, B1); PG8_BAR;
;             PG8_LDA(At, 0, 1); PG8_STAGE(PG8_SA(0, 0), a2, voffA);
;             PG8_BAR; PG8_WAIT_L(0); PG8_MMA(1, 0, At, B0); PG8_BAR; PG8_SCHED;
;             PG8_STAGE(PG8_SB(0, 1), b2 + hstep, voffB);
;             PG8_WAIT_V(6); PG8_BAR; PG8_MMA(1, 1, At, B1); PG8_BAR;
;             PG8_LDB(B0, 1, 0); PG8_SCHED; PG8_LDA(At, 1, 0); PG8_STAGE(PG8_SA(0, 1), a2 + hstep, voffA);
;             PG8_WAIT_L(8); PG8_BAR; PG8_WAIT_L(0); PG8_MMA(0, 0, At, B0); PG8_BAR; PG8_SCHED;
	s_waitcnt lgkmcnt(0)
	s_setprio 1
	s_waitcnt lgkmcnt(0)
	v_mfma_f32_16x16x32_bf16 v[120:123], v[218:221], v[152:155], v[120:123]
	v_mfma_f32_16x16x32_bf16 v[116:119], v[234:237], v[152:155], v[116:119]
	v_mfma_f32_16x16x32_bf16 v[104:107], v[218:221], v[190:193], v[104:107]
	v_mfma_f32_16x16x32_bf16 v[100:103], v[234:237], v[190:193], v[100:103]
	v_mfma_f32_16x16x32_bf16 v[88:91], v[218:221], v[198:201], v[88:91]
	v_mfma_f32_16x16x32_bf16 v[84:87], v[234:237], v[198:201], v[84:87]
	v_mfma_f32_16x16x32_bf16 v[72:75], v[218:221], v[210:213], v[72:75]
	v_mfma_f32_16x16x32_bf16 v[68:71], v[234:237], v[210:213], v[68:71]
	v_mfma_f32_16x16x32_bf16 v[120:123], v[230:233], v[186:189], v[120:123]
	v_mfma_f32_16x16x32_bf16 v[116:119], v[238:241], v[186:189], v[116:119]
	v_mfma_f32_16x16x32_bf16 v[104:107], v[230:233], v[194:197], v[104:107]
	v_mfma_f32_16x16x32_bf16 v[100:103], v[238:241], v[194:197], v[100:103]
	v_mfma_f32_16x16x32_bf16 v[88:91], v[230:233], v[202:205], v[88:91]
	v_mfma_f32_16x16x32_bf16 v[84:87], v[238:241], v[202:205], v[84:87]
	v_mfma_f32_16x16x32_bf16 v[72:75], v[230:233], v[214:217], v[72:75]
	v_mfma_f32_16x16x32_bf16 v[68:71], v[238:241], v[214:217], v[68:71]
	s_setprio 0
	s_mov_b32 m0, s45
	v_lshl_add_u64 v[244:245], s[34:35], 0, v[158:159]
	s_barrier
	ds_read_b128 v[152:155], v229 offset:16384
	ds_read_b128 v[186:189], v229 offset:17408
	ds_read_b128 v[190:193], v229 offset:18432
	ds_read_b128 v[194:197], v229 offset:19456
	ds_read_b128 v[198:201], v229 offset:20480
	ds_read_b128 v[202:205], v229 offset:21504
	ds_read_b128 v[210:213], v229 offset:22528
	ds_read_b128 v[214:217], v229 offset:23552
	global_load_lds_dwordx4 v[244:245], off
	v_lshl_add_u64 v[246:247], s[34:35], 0, v[162:163]
	s_mov_b32 m0, s46
	s_nop 0
	global_load_lds_dwordx4 v[246:247], off
	s_barrier
	s_waitcnt lgkmcnt(0)
	s_setprio 1
	s_waitcnt lgkmcnt(0)
	v_mfma_f32_16x16x32_bf16 v[64:67], v[136:139], v[152:155], v[64:67]
	v_mfma_f32_16x16x32_bf16 v[60:63], v[144:147], v[152:155], v[60:63]
	v_mfma_f32_16x16x32_bf16 v[48:51], v[136:139], v[190:193], v[48:51]
	v_mfma_f32_16x16x32_bf16 v[44:47], v[144:147], v[190:193], v[44:47]
	v_mfma_f32_16x16x32_bf16 v[32:35], v[136:139], v[198:201], v[32:35]
	v_mfma_f32_16x16x32_bf16 v[28:31], v[144:147], v[198:201], v[28:31]
	v_mfma_f32_16x16x32_bf16 v[16:19], v[136:139], v[210:213], v[16:19]
	v_mfma_f32_16x16x32_bf16 v[12:15], v[144:147], v[210:213], v[12:15]
	v_mfma_f32_16x16x32_bf16 v[64:67], v[140:143], v[186:189], v[64:67]
	v_mfma_f32_16x16x32_bf16 v[60:63], v[148:151], v[186:189], v[60:63]
	v_mfma_f32_16x16x32_bf16 v[48:51], v[140:143], v[194:197], v[48:51]
	v_mfma_f32_16x16x32_bf16 v[44:47], v[148:151], v[194:197], v[44:47]
	v_mfma_f32_16x16x32_bf16 v[32:35], v[140:143], v[202:205], v[32:35]
	v_mfma_f32_16x16x32_bf16 v[28:31], v[148:151], v[202:205], v[28:31]
	v_mfma_f32_16x16x32_bf16 v[16:19], v[140:143], v[214:217], v[16:19]
	v_mfma_f32_16x16x32_bf16 v[12:15], v[148:151], v[214:217], v[12:15]
	s_setprio 0
	s_barrier
	s_add_u32 s36, s36, s98
	s_addc_u32 s37, s37, 0
	s_mov_b32 m0, s48
	v_lshl_add_u64 v[248:249], s[36:37], 0, v[160:161]
	global_load_lds_dwordx4 v[248:249], off
	v_lshl_add_u64 v[250:251], s[36:37], 0, v[164:165]
	s_mov_b32 m0, s49
	s_nop 0
	global_load_lds_dwordx4 v[250:251], off
	s_waitcnt vmcnt(6)
	s_barrier
	s_setprio 1
	v_mfma_f32_16x16x32_bf16 v[56:59], v[218:221], v[152:155], v[56:59]
	v_mfma_f32_16x16x32_bf16 v[52:55], v[234:237], v[152:155], v[52:55]
	v_mfma_f32_16x16x32_bf16 v[40:43], v[218:221], v[190:193], v[40:43]
	v_mfma_f32_16x16x32_bf16 v[36:39], v[234:237], v[190:193], v[36:39]
	v_mfma_f32_16x16x32_bf16 v[24:27], v[218:221], v[198:201], v[24:27]
	v_mfma_f32_16x16x32_bf16 v[20:23], v[234:237], v[198:201], v[20:23]
	v_mfma_f32_16x16x32_bf16 v[8:11], v[218:221], v[210:213], v[8:11]
	v_mfma_f32_16x16x32_bf16 v[4:7], v[234:237], v[210:213], v[4:7]
	v_mfma_f32_16x16x32_bf16 v[56:59], v[230:233], v[186:189], v[56:59]
	v_mfma_f32_16x16x32_bf16 v[52:55], v[238:241], v[186:189], v[52:55]
	v_mfma_f32_16x16x32_bf16 v[40:43], v[230:233], v[194:197], v[40:43]
	v_mfma_f32_16x16x32_bf16 v[36:39], v[238:241], v[194:197], v[36:39]
	v_mfma_f32_16x16x32_bf16 v[24:27], v[230:233], v[202:205], v[24:27]
	v_mfma_f32_16x16x32_bf16 v[20:23], v[238:241], v[202:205], v[20:23]
	v_mfma_f32_16x16x32_bf16 v[8:11], v[230:233], v[214:217], v[8:11]
	v_mfma_f32_16x16x32_bf16 v[4:7], v[238:241], v[214:217], v[4:7]
	s_setprio 0
	v_add_u32_e32 v3, s52, v227
	s_barrier
	ds_read_b128 v[136:139], v3
	ds_read_b128 v[140:143], v3 offset:1024
	ds_read_b128 v[144:147], v3 offset:2048
	ds_read_b128 v[148:151], v3 offset:3072
	s_add_u32 s34, s34, s98
	s_addc_u32 s35, s35, 0
	s_mov_b32 m0, s50
	v_lshl_add_u64 v[218:219], s[34:35], 0, v[158:159]
	ds_read_b128 v[152:155], v229 offset:32768
	ds_read_b128 v[186:189], v229 offset:33792
	ds_read_b128 v[190:193], v229 offset:34816
	ds_read_b128 v[194:197], v229 offset:35840
	ds_read_b128 v[198:201], v229 offset:36864
	ds_read_b128 v[202:205], v229 offset:37888
	ds_read_b128 v[210:213], v229 offset:38912
	ds_read_b128 v[214:217], v229 offset:39936
	global_load_lds_dwordx4 v[218:219], off
	v_lshl_add_u64 v[218:219], s[34:35], 0, v[162:163]
	s_mov_b32 m0, s51
	s_nop 0
	global_load_lds_dwordx4 v[218:219], off
	s_waitcnt lgkmcnt(8)
	s_barrier
; #define PG8_STAGE(bufoff, gbase, voff) do { _Pragma("unroll") for (int _i = 0; _i < 2; ++_i) \
;         __builtin_amdgcn_global_load_lds((const unsigned*)((const char*)(gbase) + (voff)[_i]), (LAS unsigned*)(lds + (bufoff) + ldsw + _i * 8192), 16, 0, 0); } while (0)
; #define PG8_LDA(dst, b, h) do { _Pragma("unroll") for (int m = 0; m < 4; ++m) _Pragma("unroll") for (int k = 0; k < 2; ++k) dst[m][k] = *(const LAS bf16x8*)(lds + PG8_SA(b, h) + aoff + m * 2048 + k * 1024); } while (0)
; #define PG8_LDB(dst, b, h) do { _Pragma("unroll") for (int n = 0; n < 2; ++n) _Pragma("unroll") for (int k = 0; k < 2; ++k) dst[n][k] = *(const LAS bf16x8*)(lds + PG8_SB(b, h) + boff + n * 2048 + k * 1024); } while (0)
; #define PG8_MMA(ai, bj, At, Bt) do { __builtin_amdgcn_s_setprio(1); _Pragma("unroll") for (int m = 0; m < 4; ++m) _Pragma("unroll") for (int n = 0; n < 2; ++n) _Pragma("unroll") for (int k = 0; k < 2; ++k) \
;         acc[ai][bj][m][n] = __builtin_amdgcn_mfma_f32_16x16x32_bf16(Bt[n][k], At[m][k], acc[ai][bj][m][n], 0, 0, 0); __builtin_amdgcn_s_setprio(0); } while (0)
; #define PG8_WAIT_V(n) asm volatile("s_waitcnt vmcnt(" #n ")" ::: "memory")
; #define PG8_WAIT_L(n) asm volatile("s_waitcnt lgkmcnt(" #n ")" ::: "memory")
; #define PG8_BAR __builtin_amdgcn_s_barrier()
; #define PG8_SCHED __builtin_amdgcn_sched_barrier(0)
; template <class Epi, class Sched>
; __device__ __forceinline__ void gemm_phase(LAS unsigned char* lds, const Gemm g, const Sched& S, const Epi& E, const int tid) {
;     ...
;             PG8_WAIT_L(8); PG8_BAR; PG8_WAIT_L(0); PG8_MMA(0, 0, At, B0); PG8_BAR; PG8_SCHED;
;             PG8_LDB(B1, 1, 1); PG8_STAGE(PG8_SB(1, 0), b3, voffB);
;             PG8_BAR; PG8_WAIT_L(0); PG8_MMA(0, 1, At, B1); PG8_BAR;
;             PG8_LDA(At, 1, 1); PG8_STAGE(PG8_SA(1, 0), a3, voffA);
;             PG8_BAR; PG8_WAIT_L(0); PG8_MMA(1, 0, At, B0); PG8_BAR; PG8_SCHED;
;             PG8_STAGE(PG8_SB(1, 1), b3 + hstep, voffB);
;             PG8_WAIT_V(6); PG8_BAR; PG8_MMA(1, 1, At, B1); PG8_BAR;
;         }
	s_waitcnt lgkmcnt(0)
	s_setprio 1
	s_waitcnt lgkmcnt(0)
	v_mfma_f32_16x16x32_bf16 v[128:131], v[136:139], v[152:155], v[128:131]
	v_mfma_f32_16x16x32_bf16 v[124:127], v[144:147], v[152:155], v[124:127]
	v_mfma_f32_16x16x32_bf16 v[112:115], v[136:139], v[190:193], v[112:115]
	v_mfma_f32_16x16x32_bf16 v[108:111], v[144:147], v[190:193], v[108:111]
	v_mfma_f32_16x16x32_bf16 v[96:99], v[136:139], v[198:201], v[96:99]
	v_mfma_f32_16x16x32_bf16 v[92:95], v[144:147], v[198:201], v[92:95]
	v_mfma_f32_16x16x32_bf16 v[80:83], v[136:139], v[210:213], v[80:83]
	v_mfma_f32_16x16x32_bf16 v[76:79], v[144:147], v[210:213], v[76:79]
	v_mfma_f32_16x16x32_bf16 v[128:131], v[140:143], v[186:189], v[128:131]
	v_mfma_f32_16x16x32_bf16 v[124:127], v[148:151], v[186:189], v[124:127]
	v_mfma_f32_16x16x32_bf16 v[112:115], v[140:143], v[194:197], v[112:115]
	v_mfma_f32_16x16x32_bf16 v[108:111], v[148:151], v[194:197], v[108:111]
	v_mfma_f32_16x16x32_bf16 v[96:99], v[140:143], v[202:205], v[96:99]
	v_mfma_f32_16x16x32_bf16 v[92:95], v[148:151], v[202:205], v[92:95]
	v_mfma_f32_16x16x32_bf16 v[80:83], v[140:143], v[214:217], v[80:83]
	v_mfma_f32_16x16x32_bf16 v[76:79], v[148:151], v[214:217], v[76:79]
	s_setprio 0
	s_barrier
	s_mov_b32 m0, s53
	v_add_u32_e32 v3, s57, v227
	v_lshl_add_u64 v[0:1], v[0:1], 0, s[90:91]
	ds_read_b128 v[218:221], v3
	ds_read_b128 v[230:233], v3 offset:1024
	ds_read_b128 v[234:237], v3 offset:2048
	ds_read_b128 v[238:241], v3 offset:3072
	global_load_lds_dwordx4 v[0:1], off
	v_lshl_add_u64 v[0:1], v[242:243], 0, s[90:91]
	s_mov_b32 m0, s54
	s_nop 0
	global_load_lds_dwordx4 v[0:1], off
	s_barrier
	s_waitcnt lgkmcnt(0)
	s_setprio 1
	s_waitcnt lgkmcnt(0)
	v_mfma_f32_16x16x32_bf16 v[120:123], v[218:221], v[152:155], v[120:123]
	v_mfma_f32_16x16x32_bf16 v[116:119], v[234:237], v[152:155], v[116:119]
	v_mfma_f32_16x16x32_bf16 v[104:107], v[218:221], v[190:193], v[104:107]
	v_mfma_f32_16x16x32_bf16 v[100:103], v[234:237], v[190:193], v[100:103]
	v_mfma_f32_16x16x32_bf16 v[88:91], v[218:221], v[198:201], v[88:91]
	v_mfma_f32_16x16x32_bf16 v[84:87], v[234:237], v[198:201], v[84:87]
	v_mfma_f32_16x16x32_bf16 v[72:75], v[218:221], v[210:213], v[72:75]
	v_mfma_f32_16x16x32_bf16 v[68:71], v[234:237], v[210:213], v[68:71]
	v_mfma_f32_16x16x32_bf16 v[120:123], v[230:233], v[186:189], v[120:123]
	v_mfma_f32_16x16x32_bf16 v[116:119], v[238:241], v[186:189], v[116:119]
	v_mfma_f32_16x16x32_bf16 v[104:107], v[230:233], v[194:197], v[104:107]
	v_mfma_f32_16x16x32_bf16 v[100:103], v[238:241], v[194:197], v[100:103]
	v_mfma_f32_16x16x32_bf16 v[88:91], v[230:233], v[202:205], v[88:91]
	v_mfma_f32_16x16x32_bf16 v[84:87], v[238:241], v[202:205], v[84:87]
	v_mfma_f32_16x16x32_bf16 v[72:75], v[230:233], v[214:217], v[72:75]
	v_mfma_f32_16x16x32_bf16 v[68:71], v[238:241], v[214:217], v[68:71]
	s_setprio 0
	s_mov_b32 m0, s55
	v_lshl_add_u64 v[0:1], v[244:245], 0, s[90:91]
	s_barrier
	ds_read_b128 v[152:155], v229 offset:49152
	ds_read_b128 v[186:189], v229 offset:50176
	ds_read_b128 v[190:193], v229 offset:51200
	ds_read_b128 v[194:197], v229 offset:52224
	ds_read_b128 v[198:201], v229 offset:53248
	ds_read_b128 v[202:205], v229 offset:54272
	ds_read_b128 v[210:213], v229 offset:55296
	ds_read_b128 v[214:217], v229 offset:56320
	global_load_lds_dwordx4 v[0:1], off
	v_lshl_add_u64 v[0:1], v[246:247], 0, s[90:91]
	s_mov_b32 m0, s56
	s_nop 0
	global_load_lds_dwordx4 v[0:1], off
	s_barrier
	s_waitcnt lgkmcnt(0)
	s_setprio 1
	s_waitcnt lgkmcnt(0)
	v_mfma_f32_16x16x32_bf16 v[64:67], v[136:139], v[152:155], v[64:67]
	v_mfma_f32_16x16x32_bf16 v[60:63], v[144:147], v[152:155], v[60:63]
	v_mfma_f32_16x16x32_bf16 v[48:51], v[136:139], v[190:193], v[48:51]
	v_mfma_f32_16x16x32_bf16 v[44:47], v[144:147], v[190:193], v[44:47]
	v_mfma_f32_16x16x32_bf16 v[32:35], v[136:139], v[198:201], v[32:35]
	v_mfma_f32_16x16x32_bf16 v[28:31], v[144:147], v[198:201], v[28:31]
	v_mfma_f32_16x16x32_bf16 v[16:19], v[136:139], v[210:213], v[16:19]
	v_mfma_f32_16x16x32_bf16 v[12:15], v[144:147], v[210:213], v[12:15]
	v_mfma_f32_16x16x32_bf16 v[64:67], v[140:143], v[186:189], v[64:67]
	v_mfma_f32_16x16x32_bf16 v[60:63], v[148:151], v[186:189], v[60:63]
	v_mfma_f32_16x16x32_bf16 v[48:51], v[140:143], v[194:197], v[48:51]
	v_mfma_f32_16x16x32_bf16 v[44:47], v[148:151], v[194:197], v[44:47]
	v_mfma_f32_16x16x32_bf16 v[32:35], v[140:143], v[202:205], v[32:35]
	v_mfma_f32_16x16x32_bf16 v[28:31], v[148:151], v[202:205], v[28:31]
	v_mfma_f32_16x16x32_bf16 v[16:19], v[140:143], v[214:217], v[16:19]
	v_mfma_f32_16x16x32_bf16 v[12:15], v[148:151], v[214:217], v[12:15]
	s_setprio 0
	s_barrier
	s_mov_b32 m0, s58
	v_lshl_add_u64 v[0:1], v[248:249], 0, s[90:91]
	global_load_lds_dwordx4 v[0:1], off
	v_lshl_add_u64 v[0:1], v[250:251], 0, s[90:91]
	s_mov_b32 m0, s59
	s_nop 0
	global_load_lds_dwordx4 v[0:1], off
	s_waitcnt vmcnt(6)
	s_barrier
	s_setprio 1
	v_mfma_f32_16x16x32_bf16 v[56:59], v[218:221], v[152:155], v[56:59]
	v_mfma_f32_16x16x32_bf16 v[52:55], v[234:237], v[152:155], v[52:55]
	v_mfma_f32_16x16x32_bf16 v[40:43], v[218:221], v[190:193], v[40:43]
	v_mfma_f32_16x16x32_bf16 v[36:39], v[234:237], v[190:193], v[36:39]
	v_mfma_f32_16x16x32_bf16 v[24:27], v[218:221], v[198:201], v[24:27]
	v_mfma_f32_16x16x32_bf16 v[20:23], v[234:237], v[198:201], v[20:23]
	v_mfma_f32_16x16x32_bf16 v[8:11], v[218:221], v[210:213], v[8:11]
	v_mfma_f32_16x16x32_bf16 v[4:7], v[234:237], v[210:213], v[4:7]
	v_mfma_f32_16x16x32_bf16 v[56:59], v[230:233], v[186:189], v[56:59]
	v_mfma_f32_16x16x32_bf16 v[52:55], v[238:241], v[186:189], v[52:55]
	v_mfma_f32_16x16x32_bf16 v[40:43], v[230:233], v[194:197], v[40:43]
	v_mfma_f32_16x16x32_bf16 v[36:39], v[238:241], v[194:197], v[36:39]
	v_mfma_f32_16x16x32_bf16 v[24:27], v[230:233], v[202:205], v[24:27]
	v_mfma_f32_16x16x32_bf16 v[20:23], v[238:241], v[202:205], v[20:23]
	v_mfma_f32_16x16x32_bf16 v[8:11], v[230:233], v[214:217], v[8:11]
	v_mfma_f32_16x16x32_bf16 v[4:7], v[238:241], v[214:217], v[4:7]
	s_setprio 0
	s_add_u32 s4, s4, 0x100
	s_addc_u32 s5, s5, 0
	s_cmp_ge_u32 s33, s60
	s_mov_b32 s34, s33
	s_barrier
	s_cbranch_scc0 .LBB0_421

; __device__ __forceinline__ float fx_get(const long long* p, float inv) { return (float)(*(const GAS long long*)p) * inv; }
; #define PG8_SCHED __builtin_amdgcn_sched_barrier(0)
; template <class Epi, class Sched>
; __device__ __forceinline__ void gemm_phase(LAS unsigned char* lds, const Gemm g, const Sched& S, const Epi& E, const int tid) {
;     ...
;             if (E.rs2 && t == nt / 2) { PG8_SCHED; E.mid(acc, cur, wr, fr); PG8_SCHED; }
;     __device__ __forceinline__ void mid(f32x4 (&acc)[2][2][4][2], const pg8::Unit& u, int wr, int fr) const {
;         const int row0 = u.pm * 256 + wr * 64 + fr;
; #pragma unroll
;         for (int ai = 0; ai < 2; ++ai)
; #pragma unroll
;             for (int m = 0; m < 4; ++m) { int r = row0 + ai * 128 + m * 16; asm volatile("" : "+v"(r));
;                 const float a = fx_get(rs2 + r, FX_RS_INV) * (1.0f / 1024.0f) + RMS_EPS, b = fx_get(rs2 + SEQ + r, FX_RS_INV) * (1.0f / 1024.0f) + RMS_EPS;
;                 const float ratio = __builtin_amdgcn_sqrtf(b * __builtin_amdgcn_rcpf(a));
; #pragma unroll
;                 for (int bj = 0; bj < 2; ++bj)
; #pragma unroll
;                     for (int n = 0; n < 2; ++n) acc[ai][bj][m][n] *= ratio; }
.Lmy_midchk:
	s_and_b64 vcc, exec, s[24:25]
	s_cbranch_vccz .LBB0_423
	v_mov_b32_e32 v0, v184
	v_ashrrev_i32_e32 v1, 31, v0
	v_lshlrev_b64 v[0:1], 3, v[0:1]
	v_lshl_add_u64 v[136:137], s[16:17], 0, v[0:1]
	global_load_dwordx2 v[136:137], v[136:137], off
	v_lshl_add_u64 v[186:187], s[26:27], 0, v[0:1]
	global_load_dwordx2 v[186:187], v[186:187], off
	v_mov_b32_e32 v0, v182
	v_ashrrev_i32_e32 v1, 31, v0
	v_lshlrev_b64 v[0:1], 3, v[0:1]
	v_lshl_add_u64 v[138:139], s[16:17], 0, v[0:1]
	global_load_dwordx2 v[138:139], v[138:139], off
	v_lshl_add_u64 v[188:189], s[26:27], 0, v[0:1]
	global_load_dwordx2 v[188:189], v[188:189], off
	v_mov_b32_e32 v0, v180
	v_ashrrev_i32_e32 v1, 31, v0
	v_lshlrev_b64 v[0:1], 3, v[0:1]
	v_lshl_add_u64 v[140:141], s[16:17], 0, v[0:1]
	global_load_dwordx2 v[140:141], v[140:141], off
	v_lshl_add_u64 v[190:191], s[26:27], 0, v[0:1]
	global_load_dwordx2 v[190:191], v[190:191], off
	v_mov_b32_e32 v0, v178
	v_ashrrev_i32_e32 v1, 31, v0
	v_lshlrev_b64 v[0:1], 3, v[0:1]
	v_lshl_add_u64 v[142:143], s[16:17], 0, v[0:1]
	global_load_dwordx2 v[142:143], v[142:143], off
	v_lshl_add_u64 v[192:193], s[26:27], 0, v[0:1]
	global_load_dwordx2 v[192:193], v[192:193], off
	v_mov_b32_e32 v0, v176
	v_ashrrev_i32_e32 v1, 31, v0
	v_lshlrev_b64 v[0:1], 3, v[0:1]
	v_lshl_add_u64 v[144:145], s[16:17], 0, v[0:1]
	global_load_dwordx2 v[144:145], v[144:145], off
	v_lshl_add_u64 v[194:195], s[26:27], 0, v[0:1]
	global_load_dwordx2 v[194:195], v[194:195], off
	v_mov_b32_e32 v0, v174
	v_ashrrev_i32_e32 v1, 31, v0
	v_lshlrev_b64 v[0:1], 3, v[0:1]
	v_lshl_add_u64 v[146:147], s[16:17], 0, v[0:1]
	global_load_dwordx2 v[146:147], v[146:147], off
	v_lshl_add_u64 v[196:197], s[26:27], 0, v[0:1]
	global_load_dwordx2 v[196:197], v[196:197], off
	v_mov_b32_e32 v0, v172
	v_ashrrev_i32_e32 v1, 31, v0
	v_lshlrev_b64 v[0:1], 3, v[0:1]
	v_lshl_add_u64 v[148:149], s[16:17], 0, v[0:1]
	global_load_dwordx2 v[148:149], v[148:149], off
	v_lshl_add_u64 v[198:199], s[26:27], 0, v[0:1]
	global_load_dwordx2 v[198:199], v[198:199], off
	v_mov_b32_e32 v0, v170
	v_ashrrev_i32_e32 v1, 31, v0
	v_lshlrev_b64 v[0:1], 3, v[0:1]
	v_lshl_add_u64 v[150:151], s[16:17], 0, v[0:1]
	global_load_dwordx2 v[150:151], v[150:151], off
	v_lshl_add_u64 v[200:201], s[26:27], 0, v[0:1]
	global_load_dwordx2 v[200:201], v[200:201], off
	s_waitcnt vmcnt(0)
	v_xor_b32_e32 v3, v136, v137
	v_ashrrev_i32_e32 v3, 31, v3
	v_ffbh_i32_e32 v152, v137
	v_add_u32_e32 v3, 32, v3
	v_add_u32_e32 v152, -1, v152
	v_min_u32_e32 v3, v152, v3
	v_lshlrev_b64 v[136:137], v3, v[136:137]
	v_min_u32_e32 v136, 1, v136
	v_or_b32_e32 v136, v137, v136
	v_cvt_f32_i32_e32 v136, v136
	v_sub_u32_e32 v3, 32, v3
	v_ffbh_i32_e32 v137, v187
	v_add_u32_e32 v137, -1, v137
	v_ldexp_f32 v3, v136, v3
	v_xor_b32_e32 v136, v186, v187
	v_ashrrev_i32_e32 v136, 31, v136
	v_add_u32_e32 v136, 32, v136
	v_min_u32_e32 v136, v137, v136
	v_lshlrev_b64 v[186:187], v136, v[186:187]
	v_min_u32_e32 v186, 1, v186
	v_or_b32_e32 v186, v187, v186
	v_cvt_f32_i32_e32 v186, v186
	v_mul_f32_e32 v3, 0x33800000, v3
	v_fmamk_f32 v3, v3, 0x3a800000, v223
	v_sub_u32_e32 v187, 32, v136
	v_ldexp_f32 v186, v186, v187
	v_rcp_f32_e32 v187, v3
	v_mul_f32_e32 v186, 0x33800000, v186
	v_fmamk_f32 v186, v186, 0x3a800000, v223
	v_mul_f32_e32 v186, v186, v187
	v_sqrt_f32_e32 v186, v186
	s_nop 0
	v_pk_mul_f32 v[130:131], v[130:131], v[186:187] op_sel_hi:[1,0]
	v_pk_mul_f32 v[128:129], v[128:129], v[186:187] op_sel_hi:[1,0]
	v_pk_mul_f32 v[126:127], v[126:127], v[186:187] op_sel_hi:[1,0]
	v_pk_mul_f32 v[124:125], v[124:125], v[186:187] op_sel_hi:[1,0]
	v_pk_mul_f32 v[122:123], v[122:123], v[186:187] op_sel_hi:[1,0]
	v_pk_mul_f32 v[120:121], v[120:121], v[186:187] op_sel_hi:[1,0]
	v_pk_mul_f32 v[118:119], v[118:119], v[186:187] op_sel_hi:[1,0]
	v_pk_mul_f32 v[116:117], v[116:117], v[186:187] op_sel_hi:[1,0]
	v_xor_b32_e32 v153, v138, v139
	v_ashrrev_i32_e32 v153, 31, v153
	v_ffbh_i32_e32 v202, v139
	v_add_u32_e32 v153, 32, v153
	v_add_u32_e32 v202, -1, v202
	v_min_u32_e32 v153, v202, v153
	v_lshlrev_b64 v[138:139], v153, v[138:139]
	v_min_u32_e32 v138, 1, v138
	v_or_b32_e32 v138, v139, v138
	v_cvt_f32_i32_e32 v138, v138
	v_sub_u32_e32 v153, 32, v153
	v_ffbh_i32_e32 v139, v189
	v_add_u32_e32 v139, -1, v139
	v_ldexp_f32 v153, v138, v153
	v_xor_b32_e32 v138, v188, v189
	v_ashrrev_i32_e32 v138, 31, v138
	v_add_u32_e32 v138, 32, v138
	v_min_u32_e32 v138, v139, v138
	v_lshlrev_b64 v[188:189], v138, v[188:189]
	v_min_u32_e32 v188, 1, v188
	v_or_b32_e32 v188, v189, v188
	v_cvt_f32_i32_e32 v188, v188
	v_mul_f32_e32 v153, 0x33800000, v153
	v_fmamk_f32 v153, v153, 0x3a800000, v223
	v_sub_u32_e32 v189, 32, v138
	v_ldexp_f32 v188, v188, v189
	v_rcp_f32_e32 v189, v153
	v_mul_f32_e32 v188, 0x33800000, v188
	v_fmamk_f32 v188, v188, 0x3a800000, v223
	v_mul_f32_e32 v188, v188, v189
	v_sqrt_f32_e32 v188, v188
	s_nop 0
	v_pk_mul_f32 v[114:115], v[114:115], v[188:189] op_sel_hi:[1,0]
	v_pk_mul_f32 v[112:113], v[112:113], v[188:189] op_sel_hi:[1,0]
	v_pk_mul_f32 v[110:111], v[110:111], v[188:189] op_sel_hi:[1,0]
	v_pk_mul_f32 v[108:109], v[108:109], v[188:189] op_sel_hi:[1,0]
	v_pk_mul_f32 v[106:107], v[106:107], v[188:189] op_sel_hi:[1,0]
	v_pk_mul_f32 v[104:105], v[104:105], v[188:189] op_sel_hi:[1,0]
	v_pk_mul_f32 v[102:103], v[102:103], v[188:189] op_sel_hi:[1,0]
	v_pk_mul_f32 v[100:101], v[100:101], v[188:189] op_sel_hi:[1,0]
	v_xor_b32_e32 v3, v140, v141
	v_ashrrev_i32_e32 v3, 31, v3
	v_ffbh_i32_e32 v152, v141
	v_add_u32_e32 v3, 32, v3
	v_add_u32_e32 v152, -1, v152
	v_min_u32_e32 v3, v152, v3
	v_lshlrev_b64 v[140:141], v3, v[140:141]
	v_min_u32_e32 v140, 1, v140
	v_or_b32_e32 v140, v141, v140
; __device__ __forceinline__ float fx_get(const long long* p, float inv) { return (float)(*(const GAS long long*)p) * inv; }
;     __device__ __forceinline__ void mid(f32x4 (&acc)[2][2][4][2], const pg8::Unit& u, int wr, int fr) const {
;     ...
;             for (int m = 0; m < 4; ++m) { int r = row0 + ai * 128 + m * 16; asm volatile("" : "+v"(r));
;                 const float a = fx_get(rs2 + r, FX_RS_INV) * (1.0f / 1024.0f) + RMS_EPS, b = fx_get(rs2 + SEQ + r, FX_RS_INV) * (1.0f / 1024.0f) + RMS_EPS;
;                 const float ratio = __builtin_amdgcn_sqrtf(b * __builtin_amdgcn_rcpf(a));
; #pragma unroll
;                 for (int bj = 0; bj < 2; ++bj)
; #pragma unroll
;                     for (int n = 0; n < 2; ++n) acc[ai][bj][m][n] *= ratio; }
	v_cvt_f32_i32_e32 v140, v140
	v_sub_u32_e32 v3, 32, v3
	v_ffbh_i32_e32 v141, v191
	v_add_u32_e32 v141, -1, v141
	v_ldexp_f32 v3, v140, v3
	v_xor_b32_e32 v140, v190, v191
	v_ashrrev_i32_e32 v140, 31, v140
	v_add_u32_e32 v140, 32, v140
	v_min_u32_e32 v140, v141, v140
	v_lshlrev_b64 v[190:191], v140, v[190:191]
	v_min_u32_e32 v190, 1, v190
	v_or_b32_e32 v190, v191, v190
	v_cvt_f32_i32_e32 v190, v190
	v_mul_f32_e32 v3, 0x33800000, v3
	v_fmamk_f32 v3, v3, 0x3a800000, v223
	v_sub_u32_e32 v191, 32, v140
	v_ldexp_f32 v190, v190, v191
	v_rcp_f32_e32 v191, v3
	v_mul_f32_e32 v190, 0x33800000, v190
	v_fmamk_f32 v190, v190, 0x3a800000, v223
	v_mul_f32_e32 v190, v190, v191
	v_sqrt_f32_e32 v190, v190
	s_nop 0
	v_pk_mul_f32 v[98:99], v[98:99], v[190:191] op_sel_hi:[1,0]
	v_pk_mul_f32 v[96:97], v[96:97], v[190:191] op_sel_hi:[1,0]
	v_pk_mul_f32 v[94:95], v[94:95], v[190:191] op_sel_hi:[1,0]
	v_pk_mul_f32 v[92:93], v[92:93], v[190:191] op_sel_hi:[1,0]
	v_pk_mul_f32 v[90:91], v[90:91], v[190:191] op_sel_hi:[1,0]
	v_pk_mul_f32 v[88:89], v[88:89], v[190:191] op_sel_hi:[1,0]
	v_pk_mul_f32 v[86:87], v[86:87], v[190:191] op_sel_hi:[1,0]
	v_pk_mul_f32 v[84:85], v[84:85], v[190:191] op_sel_hi:[1,0]
	v_xor_b32_e32 v153, v142, v143
	v_ashrrev_i32_e32 v153, 31, v153
	v_ffbh_i32_e32 v202, v143
	v_add_u32_e32 v153, 32, v153
	v_add_u32_e32 v202, -1, v202
	v_min_u32_e32 v153, v202, v153
	v_lshlrev_b64 v[142:143], v153, v[142:143]
	v_min_u32_e32 v142, 1, v142
	v_or_b32_e32 v142, v143, v142
	v_cvt_f32_i32_e32 v142, v142
	v_sub_u32_e32 v153, 32, v153
	v_ffbh_i32_e32 v143, v193
	v_add_u32_e32 v143, -1, v143
	v_ldexp_f32 v153, v142, v153
	v_xor_b32_e32 v142, v192, v193
	v_ashrrev_i32_e32 v142, 31, v142
	v_add_u32_e32 v142, 32, v142
	v_min_u32_e32 v142, v143, v142
	v_lshlrev_b64 v[192:193], v142, v[192:193]
	v_min_u32_e32 v192, 1, v192
	v_or_b32_e32 v192, v193, v192
	v_cvt_f32_i32_e32 v192, v192
	v_mul_f32_e32 v153, 0x33800000, v153
	v_fmamk_f32 v153, v153, 0x3a800000, v223
	v_sub_u32_e32 v193, 32, v142
	v_ldexp_f32 v192, v192, v193
	v_rcp_f32_e32 v193, v153
	v_mul_f32_e32 v192, 0x33800000, v192
	v_fmamk_f32 v192, v192, 0x3a800000, v223
	v_mul_f32_e32 v192, v192, v193
	v_sqrt_f32_e32 v192, v192
	s_nop 0
	v_pk_mul_f32 v[82:83], v[82:83], v[192:193] op_sel_hi:[1,0]
	v_pk_mul_f32 v[80:81], v[80:81], v[192:193] op_sel_hi:[1,0]
	v_pk_mul_f32 v[78:79], v[78:79], v[192:193] op_sel_hi:[1,0]
	v_pk_mul_f32 v[76:77], v[76:77], v[192:193] op_sel_hi:[1,0]
	v_pk_mul_f32 v[74:75], v[74:75], v[192:193] op_sel_hi:[1,0]
	v_pk_mul_f32 v[72:73], v[72:73], v[192:193] op_sel_hi:[1,0]
	v_pk_mul_f32 v[70:71], v[70:71], v[192:193] op_sel_hi:[1,0]
	v_pk_mul_f32 v[68:69], v[68:69], v[192:193] op_sel_hi:[1,0]
	v_xor_b32_e32 v3, v144, v145
	v_ashrrev_i32_e32 v3, 31, v3
	v_ffbh_i32_e32 v152, v145
	v_add_u32_e32 v3, 32, v3
	v_add_u32_e32 v152, -1, v152
	v_min_u32_e32 v3, v152, v3
	v_lshlrev_b64 v[144:145], v3, v[144:145]
	v_min_u32_e32 v144, 1, v144
	v_or_b32_e32 v144, v145, v144
	v_cvt_f32_i32_e32 v144, v144
	v_sub_u32_e32 v3, 32, v3
	v_ffbh_i32_e32 v145, v195
	v_add_u32_e32 v145, -1, v145
	v_ldexp_f32 v3, v144, v3
	v_xor_b32_e32 v144, v194, v195
	v_ashrrev_i32_e32 v144, 31, v144
	v_add_u32_e32 v144, 32, v144
	v_min_u32_e32 v144, v145, v144
	v_lshlrev_b64 v[194:195], v144, v[194:195]
	v_min_u32_e32 v194, 1, v194
	v_or_b32_e32 v194, v195, v194
	v_cvt_f32_i32_e32 v194, v194
	v_mul_f32_e32 v3, 0x33800000, v3
	v_fmamk_f32 v3, v3, 0x3a800000, v223
	v_sub_u32_e32 v195, 32, v144
	v_ldexp_f32 v194, v194, v195
	v_rcp_f32_e32 v195, v3
	v_mul_f32_e32 v194, 0x33800000, v194
	v_fmamk_f32 v194, v194, 0x3a800000, v223
	v_mul_f32_e32 v194, v194, v195
	v_sqrt_f32_e32 v194, v194
	s_nop 0
	v_pk_mul_f32 v[66:67], v[66:67], v[194:195] op_sel_hi:[1,0]
	v_pk_mul_f32 v[64:65], v[64:65], v[194:195] op_sel_hi:[1,0]
	v_pk_mul_f32 v[62:63], v[62:63], v[194:195] op_sel_hi:[1,0]
	v_pk_mul_f32 v[60:61], v[60:61], v[194:195] op_sel_hi:[1,0]
	v_pk_mul_f32 v[58:59], v[58:59], v[194:195] op_sel_hi:[1,0]
	v_pk_mul_f32 v[56:57], v[56:57], v[194:195] op_sel_hi:[1,0]
	v_pk_mul_f32 v[54:55], v[54:55], v[194:195] op_sel_hi:[1,0]
	v_pk_mul_f32 v[52:53], v[52:53], v[194:195] op_sel_hi:[1,0]
	v_xor_b32_e32 v153, v146, v147
	v_ashrrev_i32_e32 v153, 31, v153
	v_ffbh_i32_e32 v202, v147
	v_add_u32_e32 v153, 32, v153
	v_add_u32_e32 v202, -1, v202
; __device__ __forceinline__ float fx_get(const long long* p, float inv) { return (float)(*(const GAS long long*)p) * inv; }
;     __device__ __forceinline__ void mid(f32x4 (&acc)[2][2][4][2], const pg8::Unit& u, int wr, int fr) const {
;     ...
;             for (int m = 0; m < 4; ++m) { int r = row0 + ai * 128 + m * 16; asm volatile("" : "+v"(r));
;                 const float a = fx_get(rs2 + r, FX_RS_INV) * (1.0f / 1024.0f) + RMS_EPS, b = fx_get(rs2 + SEQ + r, FX_RS_INV) * (1.0f / 1024.0f) + RMS_EPS;
;                 const float ratio = __builtin_amdgcn_sqrtf(b * __builtin_amdgcn_rcpf(a));
; #pragma unroll
;                 for (int bj = 0; bj < 2; ++bj)
; #pragma unroll
;                     for (int n = 0; n < 2; ++n) acc[ai][bj][m][n] *= ratio; }
	v_min_u32_e32 v153, v202, v153
	v_lshlrev_b64 v[146:147], v153, v[146:147]
	v_min_u32_e32 v146, 1, v146
	v_or_b32_e32 v146, v147, v146
	v_cvt_f32_i32_e32 v146, v146
	v_sub_u32_e32 v153, 32, v153
	v_ffbh_i32_e32 v147, v197
	v_add_u32_e32 v147, -1, v147
	v_ldexp_f32 v153, v146, v153
	v_xor_b32_e32 v146, v196, v197
	v_ashrrev_i32_e32 v146, 31, v146
	v_add_u32_e32 v146, 32, v146
	v_min_u32_e32 v146, v147, v146
	v_lshlrev_b64 v[196:197], v146, v[196:197]
	v_min_u32_e32 v196, 1, v196
	v_or_b32_e32 v196, v197, v196
	v_cvt_f32_i32_e32 v196, v196
	v_mul_f32_e32 v153, 0x33800000, v153
	v_fmamk_f32 v153, v153, 0x3a800000, v223
	v_sub_u32_e32 v197, 32, v146
	v_ldexp_f32 v196, v196, v197
	v_rcp_f32_e32 v197, v153
	v_mul_f32_e32 v196, 0x33800000, v196
	v_fmamk_f32 v196, v196, 0x3a800000, v223
	v_mul_f32_e32 v196, v196, v197
	v_sqrt_f32_e32 v196, v196
	s_nop 0
	v_pk_mul_f32 v[50:51], v[50:51], v[196:197] op_sel_hi:[1,0]
	v_pk_mul_f32 v[48:49], v[48:49], v[196:197] op_sel_hi:[1,0]
	v_pk_mul_f32 v[46:47], v[46:47], v[196:197] op_sel_hi:[1,0]
	v_pk_mul_f32 v[44:45], v[44:45], v[196:197] op_sel_hi:[1,0]
	v_pk_mul_f32 v[42:43], v[42:43], v[196:197] op_sel_hi:[1,0]
	v_pk_mul_f32 v[40:41], v[40:41], v[196:197] op_sel_hi:[1,0]
	v_pk_mul_f32 v[38:39], v[38:39], v[196:197] op_sel_hi:[1,0]
	v_pk_mul_f32 v[36:37], v[36:37], v[196:197] op_sel_hi:[1,0]
	v_xor_b32_e32 v3, v148, v149
	v_ashrrev_i32_e32 v3, 31, v3
	v_ffbh_i32_e32 v152, v149
	v_add_u32_e32 v3, 32, v3
	v_add_u32_e32 v152, -1, v152
	v_min_u32_e32 v3, v152, v3
	v_lshlrev_b64 v[148:149], v3, v[148:149]
	v_min_u32_e32 v148, 1, v148
	v_or_b32_e32 v148, v149, v148
	v_cvt_f32_i32_e32 v148, v148
	v_sub_u32_e32 v3, 32, v3
	v_ffbh_i32_e32 v149, v199
	v_add_u32_e32 v149, -1, v149
	v_ldexp_f32 v3, v148, v3
	v_xor_b32_e32 v148, v198, v199
	v_ashrrev_i32_e32 v148, 31, v148
	v_add_u32_e32 v148, 32, v148
	v_min_u32_e32 v148, v149, v148
	v_lshlrev_b64 v[198:199], v148, v[198:199]
	v_min_u32_e32 v198, 1, v198
	v_or_b32_e32 v198, v199, v198
	v_cvt_f32_i32_e32 v198, v198
	v_mul_f32_e32 v3, 0x33800000, v3
	v_fmamk_f32 v3, v3, 0x3a800000, v223
	v_sub_u32_e32 v199, 32, v148
	v_ldexp_f32 v198, v198, v199
	v_rcp_f32_e32 v199, v3
	v_mul_f32_e32 v198, 0x33800000, v198
	v_fmamk_f32 v198, v198, 0x3a800000, v223
	v_mul_f32_e32 v198, v198, v199
	v_sqrt_f32_e32 v198, v198
	s_nop 0
	v_pk_mul_f32 v[34:35], v[34:35], v[198:199] op_sel_hi:[1,0]
	v_pk_mul_f32 v[32:33], v[32:33], v[198:199] op_sel_hi:[1,0]
	v_pk_mul_f32 v[30:31], v[30:31], v[198:199] op_sel_hi:[1,0]
	v_pk_mul_f32 v[28:29], v[28:29], v[198:199] op_sel_hi:[1,0]
	v_pk_mul_f32 v[26:27], v[26:27], v[198:199] op_sel_hi:[1,0]
	v_pk_mul_f32 v[24:25], v[24:25], v[198:199] op_sel_hi:[1,0]
	v_pk_mul_f32 v[22:23], v[22:23], v[198:199] op_sel_hi:[1,0]
	v_pk_mul_f32 v[20:21], v[20:21], v[198:199] op_sel_hi:[1,0]
	v_xor_b32_e32 v153, v150, v151
	v_ashrrev_i32_e32 v153, 31, v153
	v_ffbh_i32_e32 v202, v151
	v_add_u32_e32 v153, 32, v153
	v_add_u32_e32 v202, -1, v202
	v_min_u32_e32 v153, v202, v153
	v_lshlrev_b64 v[150:151], v153, v[150:151]
	v_min_u32_e32 v150, 1, v150
	v_or_b32_e32 v150, v151, v150
	v_cvt_f32_i32_e32 v150, v150
	v_sub_u32_e32 v153, 32, v153
	v_ffbh_i32_e32 v151, v201
	v_add_u32_e32 v151, -1, v151
	v_ldexp_f32 v153, v150, v153
	v_xor_b32_e32 v150, v200, v201
	v_ashrrev_i32_e32 v150, 31, v150
	v_add_u32_e32 v150, 32, v150
	v_min_u32_e32 v150, v151, v150
	v_lshlrev_b64 v[200:201], v150, v[200:201]
	v_min_u32_e32 v200, 1, v200
	v_or_b32_e32 v200, v201, v200
	v_cvt_f32_i32_e32 v200, v200
	v_mul_f32_e32 v153, 0x33800000, v153
	v_fmamk_f32 v153, v153, 0x3a800000, v223
	v_sub_u32_e32 v201, 32, v150
	v_ldexp_f32 v200, v200, v201
	v_rcp_f32_e32 v201, v153
	v_mul_f32_e32 v200, 0x33800000, v200
	v_fmamk_f32 v200, v200, 0x3a800000, v223
	v_mul_f32_e32 v200, v200, v201
	v_sqrt_f32_e32 v200, v200
	s_nop 0
	v_pk_mul_f32 v[18:19], v[18:19], v[200:201] op_sel_hi:[1,0]
	v_pk_mul_f32 v[16:17], v[16:17], v[200:201] op_sel_hi:[1,0]
	v_pk_mul_f32 v[14:15], v[14:15], v[200:201] op_sel_hi:[1,0]
	v_pk_mul_f32 v[12:13], v[12:13], v[200:201] op_sel_hi:[1,0]
	v_pk_mul_f32 v[10:11], v[10:11], v[200:201] op_sel_hi:[1,0]
	v_pk_mul_f32 v[8:9], v[8:9], v[200:201] op_sel_hi:[1,0]
	v_pk_mul_f32 v[6:7], v[6:7], v[200:201] op_sel_hi:[1,0]
	v_pk_mul_f32 v[4:5], v[4:5], v[200:201] op_sel_hi:[1,0]
	s_branch .LBB0_423
